# v39 + gMLP block LayerNorm (before G4): the 30 later gain/bias loads of a 256x256 block issued at its head (was 16 serial load-wait-store round trips per block behind the in-place stores)
# baseline (speedup 1.0000x reference)
; __device__ __forceinline__ void gm_ln_block(bf16_t* Vt, const float* S1, const float* S2, const float* lng, const float* lnb, int c0, int t0, int tid) {
;     const int tt = t0 + (tid & 31) * 8, r0 = tid >> 5;
;     float mu[8], rs[8];
;     { const f32x4 a0 = *(const f32x4*)(S1 + tt), a1 = *(const f32x4*)(S1 + tt + 4), b0 = *(const f32x4*)(S2 + tt), b1 = *(const f32x4*)(S2 + tt + 4);
; #pragma unroll
;       for (int e = 0; e < 8; ++e) { const float s1 = e < 4 ? a0[e & 3] : a1[e & 3], s2 = e < 4 ? b0[e & 3] : b1[e & 3]; mu[e] = s1 * (1.f / GMH); rs[e] = 1.0f / sqrtf(fmaxf(s2 * (1.f / GMH) - mu[e] * mu[e], 0.f) + EPS); } }
; #pragma unroll
;     for (int k0 = 0; k0 < 16; k0 += 8) {
;         u32x4 raw[8];
; #pragma unroll
;         for (int k = 0; k < 8; ++k) raw[k] = *(const u32x4*)(Vt + (size_t)(c0 + r0 + 16 * (k0 + k)) * MALL + tt);
.LBB0_423:
	v_mov_b64_e32 v[0:1], s[68:69]
	v_cmp_lt_i64_e32 vcc, s[20:21], v[0:1]
	s_mov_b64 s[6:7], -1
	s_cbranch_vccz .LBB0_420
	v_lshl_or_b32 v16, s55, 8, v68
	v_ashrrev_i32_e32 v17, 31, v16
	v_lshlrev_b64 v[4:5], 2, v[16:17]
	v_lshl_add_u64 v[0:1], s[8:9], 0, v[4:5]
	v_lshl_add_u64 v[4:5], s[16:17], 0, v[4:5]
	s_load_dwordx4 s[24:27], s[4:5], 0x90
	global_load_dwordx4 v[8:11], v[0:1], off
	s_nop 0
	global_load_dwordx4 v[0:3], v[0:1], off offset:16
	s_nop 0
	global_load_dwordx4 v[12:15], v[4:5], off
	s_nop 0
	global_load_dwordx4 v[4:7], v[4:5], off offset:16
	v_lshl_add_u32 v52, s54, 8, v69
	v_lshl_add_u64 v[48:49], v[16:17], 1, s[14:15]
	s_waitcnt lgkmcnt(0)
	s_add_u32 s22, s24, s18
	s_addc_u32 s23, s25, s19
	s_add_u32 s24, s26, s18
	s_mov_b32 s26, 0x3a000000
	v_ashrrev_i32_e32 v53, 31, v52
	s_addc_u32 s25, s27, s19
	s_add_u32 s20, s20, s1
	s_addc_u32 s21, s21, s56
	s_waitcnt vmcnt(0)
	v_mov_b32_e32 v19, v2
	s_waitcnt vmcnt(0)
	v_mov_b32_e32 v18, v6
	v_pk_mul_f32 v[28:29], v[18:19], s[26:27] op_sel_hi:[1,0]
	s_nop 0
	v_fma_f32 v2, -v29, v29, v28
	v_max_f32_e32 v2, 0, v2
	v_add_f32_e32 v2, 0x358637bd, v2
	v_cmp_gt_f32_e32 vcc, s91, v2
	v_mul_f32_e32 v6, 0x4f800000, v2
	s_nop 0
	v_cndmask_b32_e32 v2, v2, v6, vcc
	v_sqrt_f32_e32 v6, v2
	s_nop 0
	v_add_u32_e32 v18, -1, v6
	v_fma_f32 v19, -v18, v6, v2
	v_cmp_ge_f32_e64 s[6:7], 0, v19
	v_add_u32_e32 v19, 1, v6
	s_nop 0
	v_cndmask_b32_e64 v18, v6, v18, s[6:7]
	v_fma_f32 v6, -v19, v6, v2
	v_cmp_lt_f32_e64 s[6:7], 0, v6
	s_nop 1
	v_cndmask_b32_e64 v6, v18, v19, s[6:7]
	v_mul_f32_e32 v18, 0x37800000, v6
	v_cndmask_b32_e32 v6, v6, v18, vcc
	v_cmp_class_f32_e32 vcc, v2, v254
	s_nop 1
	v_cndmask_b32_e32 v2, v6, v2, vcc
	v_div_scale_f32 v6, s[2:3], v2, v2, 1.0
	v_rcp_f32_e32 v18, v6
	s_nop 0
	v_fma_f32 v19, -v6, v18, 1.0
	v_fmac_f32_e32 v18, v19, v18
	v_div_scale_f32 v19, vcc, 1.0, v2, 1.0
	v_mul_f32_e32 v20, v19, v18
	v_fma_f32 v21, -v6, v20, v19
	v_fmac_f32_e32 v20, v21, v18
	v_fma_f32 v6, -v6, v20, v19
	v_div_fmas_f32 v6, v6, v18, v20
	v_mov_b32_e32 v18, v5
	v_mov_b32_e32 v19, v1
	v_pk_mul_f32 v[30:31], v[18:19], s[26:27] op_sel_hi:[1,0]
	v_div_fixup_f32 v28, v6, v2, 1.0
	v_fma_f32 v1, -v31, v31, v30
	v_max_f32_e32 v1, 0, v1
	v_add_f32_e32 v1, 0x358637bd, v1
	v_cmp_gt_f32_e32 vcc, s91, v1
	v_mul_f32_e32 v2, 0x4f800000, v1
	s_nop 0
	v_cndmask_b32_e32 v1, v1, v2, vcc
	v_sqrt_f32_e32 v2, v1
	s_nop 0
	v_add_u32_e32 v5, -1, v2
	v_fma_f32 v6, -v5, v2, v1
	v_cmp_ge_f32_e64 s[6:7], 0, v6
	v_add_u32_e32 v6, 1, v2
	s_nop 0
	v_cndmask_b32_e64 v5, v2, v5, s[6:7]
	v_fma_f32 v2, -v6, v2, v1
	v_cmp_lt_f32_e64 s[6:7], 0, v2
	s_nop 1
	v_cndmask_b32_e64 v2, v5, v6, s[6:7]
	v_mul_f32_e32 v5, 0x37800000, v2
	v_cndmask_b32_e32 v2, v2, v5, vcc
	v_cmp_class_f32_e32 vcc, v1, v254
	s_nop 1
	v_cndmask_b32_e32 v1, v2, v1, vcc
	v_div_scale_f32 v2, s[2:3], v1, v1, 1.0
	v_rcp_f32_e32 v5, v2
	s_nop 0
	v_fma_f32 v6, -v2, v5, 1.0
	v_fmac_f32_e32 v5, v6, v5
	v_div_scale_f32 v6, vcc, 1.0, v1, 1.0
	v_mul_f32_e32 v18, v6, v5
	v_fma_f32 v19, -v2, v18, v6
	v_fmac_f32_e32 v18, v19, v5
	v_fma_f32 v2, -v2, v18, v6
	v_div_fmas_f32 v2, v2, v5, v18
	v_mov_b32_e32 v5, v0
	v_pk_mul_f32 v[32:33], v[4:5], s[26:27] op_sel_hi:[1,0]
	v_div_fixup_f32 v30, v2, v1, 1.0
	v_fma_f32 v0, -v33, v33, v32
	v_max_f32_e32 v0, 0, v0
	v_add_f32_e32 v0, 0x358637bd, v0
	v_cmp_gt_f32_e32 vcc, s91, v0
	v_mul_f32_e32 v1, 0x4f800000, v0
	s_nop 0
	v_cndmask_b32_e32 v0, v0, v1, vcc
	v_sqrt_f32_e32 v1, v0
	s_nop 0
	v_add_u32_e32 v2, -1, v1
	v_fma_f32 v4, -v2, v1, v0
	v_cmp_ge_f32_e64 s[6:7], 0, v4
	v_add_u32_e32 v4, 1, v1
	s_nop 0
	v_cndmask_b32_e64 v2, v1, v2, s[6:7]
	v_fma_f32 v1, -v4, v1, v0
	v_cmp_lt_f32_e64 s[6:7], 0, v1
	s_nop 1
	v_cndmask_b32_e64 v1, v2, v4, s[6:7]
	v_mul_f32_e32 v2, 0x37800000, v1
	v_cndmask_b32_e32 v1, v1, v2, vcc
	v_cmp_class_f32_e32 vcc, v0, v254
	s_nop 1
	v_cndmask_b32_e32 v0, v1, v0, vcc
	v_div_scale_f32 v1, s[2:3], v0, v0, 1.0
	v_rcp_f32_e32 v2, v1
	s_nop 0
	v_fma_f32 v4, -v1, v2, 1.0
	v_fmac_f32_e32 v2, v4, v2
	v_div_scale_f32 v4, vcc, 1.0, v0, 1.0
	v_mul_f32_e32 v5, v4, v2
	v_fma_f32 v6, -v1, v5, v4
	v_fmac_f32_e32 v5, v6, v2
	v_fma_f32 v1, -v1, v5, v4
	v_div_fmas_f32 v1, v1, v2, v5
	v_div_fixup_f32 v32, v1, v0, 1.0
	v_mov_b32_e32 v0, v15
	v_mov_b32_e32 v1, v11
	v_pk_mul_f32 v[34:35], v[0:1], s[26:27] op_sel_hi:[1,0]
	v_mov_b32_e32 v15, v10
	v_fma_f32 v0, -v35, v35, v34
	v_max_f32_e32 v0, 0, v0
	v_add_f32_e32 v0, 0x358637bd, v0
	v_cmp_gt_f32_e32 vcc, s91, v0
	v_mul_f32_e32 v1, 0x4f800000, v0
	v_pk_mul_f32 v[36:37], v[14:15], s[26:27] op_sel_hi:[1,0]
	v_cndmask_b32_e32 v0, v0, v1, vcc
	v_sqrt_f32_e32 v1, v0
	s_nop 0
	v_add_u32_e32 v2, -1, v1
	v_fma_f32 v4, -v2, v1, v0
	v_cmp_ge_f32_e64 s[6:7], 0, v4
	v_add_u32_e32 v4, 1, v1
	s_nop 0
	v_cndmask_b32_e64 v2, v1, v2, s[6:7]
	v_fma_f32 v1, -v4, v1, v0
	v_cmp_lt_f32_e64 s[6:7], 0, v1
	s_nop 1
	v_cndmask_b32_e64 v1, v2, v4, s[6:7]
	v_mul_f32_e32 v2, 0x37800000, v1
	v_cndmask_b32_e32 v1, v1, v2, vcc
	v_cmp_class_f32_e32 vcc, v0, v254
	s_nop 1
	v_cndmask_b32_e32 v0, v1, v0, vcc
	v_div_scale_f32 v1, s[2:3], v0, v0, 1.0
	v_rcp_f32_e32 v2, v1
	s_nop 0
	v_fma_f32 v4, -v1, v2, 1.0
	v_fmac_f32_e32 v2, v4, v2
	v_div_scale_f32 v4, vcc, 1.0, v0, 1.0
	v_mul_f32_e32 v5, v4, v2
	v_fma_f32 v6, -v1, v5, v4
	v_fmac_f32_e32 v5, v6, v2
	v_fma_f32 v1, -v1, v5, v4
	v_div_fmas_f32 v1, v1, v2, v5
	v_div_fixup_f32 v34, v1, v0, 1.0
	v_fma_f32 v0, -v37, v37, v36
	v_max_f32_e32 v0, 0, v0
	v_add_f32_e32 v0, 0x358637bd, v0
	v_cmp_gt_f32_e32 vcc, s91, v0
	v_mul_f32_e32 v1, 0x4f800000, v0
	s_nop 0
	v_cndmask_b32_e32 v0, v0, v1, vcc
	v_sqrt_f32_e32 v1, v0
	s_nop 0
	v_add_u32_e32 v2, -1, v1
	v_fma_f32 v4, -v2, v1, v0
; __device__ __forceinline__ void gm_ln_block(bf16_t* Vt, const float* S1, const float* S2, const float* lng, const float* lnb, int c0, int t0, int tid) {
;     const int tt = t0 + (tid & 31) * 8, r0 = tid >> 5;
;     float mu[8], rs[8];
;     { const f32x4 a0 = *(const f32x4*)(S1 + tt), a1 = *(const f32x4*)(S1 + tt + 4), b0 = *(const f32x4*)(S2 + tt), b1 = *(const f32x4*)(S2 + tt + 4);
; #pragma unroll
;       for (int e = 0; e < 8; ++e) { const float s1 = e < 4 ? a0[e & 3] : a1[e & 3], s2 = e < 4 ? b0[e & 3] : b1[e & 3]; mu[e] = s1 * (1.f / GMH); rs[e] = 1.0f / sqrtf(fmaxf(s2 * (1.f / GMH) - mu[e] * mu[e], 0.f) + EPS); } }
; #pragma unroll
;     for (int k0 = 0; k0 < 16; k0 += 8) {
;         u32x4 raw[8];
; #pragma unroll
;         for (int k = 0; k < 8; ++k) raw[k] = *(const u32x4*)(Vt + (size_t)(c0 + r0 + 16 * (k0 + k)) * MALL + tt);
	v_cmp_ge_f32_e64 s[6:7], 0, v4
	v_add_u32_e32 v4, 1, v1
	s_nop 0
	v_cndmask_b32_e64 v2, v1, v2, s[6:7]
	v_fma_f32 v1, -v4, v1, v0
	v_cmp_lt_f32_e64 s[6:7], 0, v1
	s_nop 1
	v_cndmask_b32_e64 v1, v2, v4, s[6:7]
	v_mul_f32_e32 v2, 0x37800000, v1
	v_cndmask_b32_e32 v1, v1, v2, vcc
	v_cmp_class_f32_e32 vcc, v0, v254
	s_nop 1
	v_cndmask_b32_e32 v0, v1, v0, vcc
	v_div_scale_f32 v1, s[2:3], v0, v0, 1.0
	v_rcp_f32_e32 v2, v1
	s_nop 0
	v_fma_f32 v4, -v1, v2, 1.0
	v_fmac_f32_e32 v2, v4, v2
	v_div_scale_f32 v4, vcc, 1.0, v0, 1.0
	v_mul_f32_e32 v5, v4, v2
	v_fma_f32 v6, -v1, v5, v4
	v_fmac_f32_e32 v5, v6, v2
	v_fma_f32 v1, -v1, v5, v4
	v_div_fmas_f32 v1, v1, v2, v5
	v_div_fixup_f32 v36, v1, v0, 1.0
	v_mov_b32_e32 v0, v13
	v_mov_b32_e32 v1, v9
	v_pk_mul_f32 v[38:39], v[0:1], s[26:27] op_sel_hi:[1,0]
	v_mov_b32_e32 v13, v8
	v_fma_f32 v0, -v39, v39, v38
	v_max_f32_e32 v0, 0, v0
	v_add_f32_e32 v0, 0x358637bd, v0
	v_cmp_gt_f32_e32 vcc, s91, v0
	v_mul_f32_e32 v1, 0x4f800000, v0
	v_pk_mul_f32 v[40:41], v[12:13], s[26:27] op_sel_hi:[1,0]
	v_cndmask_b32_e32 v0, v0, v1, vcc
	v_sqrt_f32_e32 v1, v0
	s_nop 0
	v_add_u32_e32 v2, -1, v1
	v_fma_f32 v4, -v2, v1, v0
	v_cmp_ge_f32_e64 s[6:7], 0, v4
	v_add_u32_e32 v4, 1, v1
	s_nop 0
	v_cndmask_b32_e64 v2, v1, v2, s[6:7]
	v_fma_f32 v1, -v4, v1, v0
	v_cmp_lt_f32_e64 s[6:7], 0, v1
	s_nop 1
	v_cndmask_b32_e64 v1, v2, v4, s[6:7]
	v_mul_f32_e32 v2, 0x37800000, v1
	v_cndmask_b32_e32 v1, v1, v2, vcc
	v_cmp_class_f32_e32 vcc, v0, v254
	s_nop 1
	v_cndmask_b32_e32 v0, v1, v0, vcc
	v_div_scale_f32 v1, s[2:3], v0, v0, 1.0
	v_rcp_f32_e32 v2, v1
	s_nop 0
	v_fma_f32 v4, -v1, v2, 1.0
	v_fmac_f32_e32 v2, v4, v2
	v_div_scale_f32 v4, vcc, 1.0, v0, 1.0
	v_mul_f32_e32 v5, v4, v2
	v_fma_f32 v6, -v1, v5, v4
	v_fmac_f32_e32 v5, v6, v2
	v_fma_f32 v1, -v1, v5, v4
	v_div_fmas_f32 v1, v1, v2, v5
	v_div_fixup_f32 v38, v1, v0, 1.0
	v_fma_f32 v0, -v41, v41, v40
	v_max_f32_e32 v0, 0, v0
	v_add_f32_e32 v0, 0x358637bd, v0
	v_cmp_gt_f32_e32 vcc, s91, v0
	v_mul_f32_e32 v1, 0x4f800000, v0
	s_nop 0
	v_cndmask_b32_e32 v0, v0, v1, vcc
	v_sqrt_f32_e32 v1, v0
	s_nop 0
	v_add_u32_e32 v2, -1, v1
	v_fma_f32 v4, -v2, v1, v0
	v_cmp_ge_f32_e64 s[6:7], 0, v4
	v_add_u32_e32 v4, 1, v1
	s_nop 0
	v_cndmask_b32_e64 v2, v1, v2, s[6:7]
	v_fma_f32 v1, -v4, v1, v0
	v_cmp_lt_f32_e64 s[6:7], 0, v1
	s_nop 1
	v_cndmask_b32_e64 v1, v2, v4, s[6:7]
	v_mul_f32_e32 v2, 0x37800000, v1
	v_cndmask_b32_e32 v1, v1, v2, vcc
	v_cmp_class_f32_e32 vcc, v0, v254
	s_nop 1
	v_cndmask_b32_e32 v0, v1, v0, vcc
	v_div_scale_f32 v1, s[2:3], v0, v0, 1.0
	v_rcp_f32_e32 v2, v1
	s_nop 0
	v_fma_f32 v4, -v1, v2, 1.0
	v_fmac_f32_e32 v2, v4, v2
	v_div_scale_f32 v4, vcc, 1.0, v0, 1.0
	v_mul_f32_e32 v5, v4, v2
	v_fma_f32 v6, -v1, v5, v4
	v_fmac_f32_e32 v5, v6, v2
	v_fma_f32 v1, -v1, v5, v4
	v_div_fmas_f32 v1, v1, v2, v5
	v_mov_b32_e32 v2, v7
	v_pk_mul_f32 v[42:43], v[2:3], s[26:27] op_sel_hi:[1,0]
	v_div_fixup_f32 v40, v1, v0, 1.0
	v_fma_f32 v0, -v43, v43, v42
	v_max_f32_e32 v0, 0, v0
	v_add_f32_e32 v0, 0x358637bd, v0
	v_cmp_gt_f32_e32 vcc, s91, v0
	v_mul_f32_e32 v1, 0x4f800000, v0
	s_nop 0
	v_cndmask_b32_e32 v0, v0, v1, vcc
	v_sqrt_f32_e32 v1, v0
	s_nop 0
	v_add_u32_e32 v2, -1, v1
	v_fma_f32 v3, -v2, v1, v0
	v_cmp_ge_f32_e64 s[6:7], 0, v3
	v_add_u32_e32 v3, 1, v1
	s_nop 0
	v_cndmask_b32_e64 v2, v1, v2, s[6:7]
	v_fma_f32 v1, -v3, v1, v0
	v_cmp_lt_f32_e64 s[6:7], 0, v1
	s_nop 1
	v_cndmask_b32_e64 v1, v2, v3, s[6:7]
	s_mov_b32 s6, 0x8800
	v_mad_i64_i32 v[66:67], s[2:3], v52, s6, v[48:49]
	global_load_dwordx4 v[44:47], v[66:67], off
	v_mul_f32_e32 v2, 0x37800000, v1
	v_cndmask_b32_e32 v1, v1, v2, vcc
	v_cmp_class_f32_e32 vcc, v0, v254
	s_nop 1
	v_cndmask_b32_e32 v0, v1, v0, vcc
	v_div_scale_f32 v1, s[2:3], v0, v0, 1.0
	v_rcp_f32_e32 v2, v1
	s_nop 0
	v_fma_f32 v3, -v1, v2, 1.0
	v_fmac_f32_e32 v2, v3, v2
	v_div_scale_f32 v3, vcc, 1.0, v0, 1.0
	v_mul_f32_e32 v4, v3, v2
	v_fma_f32 v5, -v1, v4, v3
	v_fmac_f32_e32 v4, v5, v2
	v_fma_f32 v1, -v1, v4, v3
	v_div_fmas_f32 v1, v1, v2, v4
	v_div_fixup_f32 v42, v1, v0, 1.0
	v_add_u32_e32 v0, 16, v52
	v_mad_i64_i32 v[64:65], s[2:3], v0, s6, v[48:49]
	global_load_dwordx4 v[24:27], v[64:65], off
	v_add_u32_e32 v0, 32, v52
	v_mad_i64_i32 v[62:63], s[2:3], v0, s6, v[48:49]
	v_add_u32_e32 v0, 48, v52
	v_mad_i64_i32 v[60:61], s[2:3], v0, s6, v[48:49]
	v_add_u32_e32 v0, 64, v52
	v_mad_i64_i32 v[58:59], s[2:3], v0, s6, v[48:49]
	v_add_u32_e32 v0, 0x50, v52
	v_mad_i64_i32 v[56:57], s[2:3], v0, s6, v[48:49]
	v_add_u32_e32 v0, 0x60, v52
	v_mad_i64_i32 v[54:55], s[2:3], v0, s6, v[48:49]
	v_add_u32_e32 v0, 0x70, v52
	v_mad_i64_i32 v[50:51], s[2:3], v0, s6, v[48:49]
	global_load_dwordx4 v[20:23], v[62:63], off
	global_load_dwordx4 v[16:19], v[60:61], off
	global_load_dwordx4 v[12:15], v[58:59], off
	global_load_dwordx4 v[8:11], v[56:57], off
	global_load_dwordx4 v[4:7], v[54:55], off
	global_load_dwordx4 v[0:3], v[50:51], off
	s_waitcnt vmcnt(7)
; __device__ __forceinline__ void unpack8(const u32x4 w, float* f) { f[0] = bf_lo(w.x); f[1] = bf_hi(w.x); f[2] = bf_lo(w.y); f[3] = bf_hi(w.y); f[4] = bf_lo(w.z); f[5] = bf_hi(w.z); f[6] = bf_lo(w.w); f[7] = bf_hi(w.w); }
; __device__ __forceinline__ u32x4 pack8(const float* f) { u32x4 w; w.x = cvt_pk_bf16(f[0], f[1]); w.y = cvt_pk_bf16(f[2], f[3]); w.z = cvt_pk_bf16(f[4], f[5]); w.w = cvt_pk_bf16(f[6], f[7]); return w; }
; __device__ __forceinline__ void gm_ln_block(bf16_t* Vt, const float* S1, const float* S2, const float* lng, const float* lnb, int c0, int t0, int tid) {
;     ...
; #pragma unroll
;     for (int k0 = 0; k0 < 16; k0 += 8) {
;         u32x4 raw[8];
; #pragma unroll
;         for (int k = 0; k < 8; ++k) raw[k] = *(const u32x4*)(Vt + (size_t)(c0 + r0 + 16 * (k0 + k)) * MALL + tt);
; #pragma unroll
;         for (int k = 0; k < 8; ++k) { const int c = c0 + r0 + 16 * (k0 + k); float x[8]; unpack8(raw[k], x); const float g = lng[c], b = lnb[c];
; #pragma unroll
;             for (int e = 0; e < 8; ++e) x[e] = (x[e] - mu[e]) * (rs[e] * g) + b;
;             *(u32x4*)(Vt + (size_t)c * MALL + tt) = pack8(x); }
;     }
	v_lshlrev_b32_e32 v74, 16, v46
	v_and_b32_e32 v75, 0xffff0000, v46
	v_lshlrev_b32_e32 v76, 16, v47
	v_and_b32_e32 v77, 0xffff0000, v47
	v_lshlrev_b64 v[46:47], 2, v[52:53]
	v_lshlrev_b32_e32 v70, 16, v44
	v_and_b32_e32 v71, 0xffff0000, v44
	v_lshlrev_b32_e32 v72, 16, v45
	v_and_b32_e32 v73, 0xffff0000, v45
	v_lshl_add_u64 v[44:45], s[22:23], 0, v[46:47]
	global_load_dword v53, v[44:45], off
	v_lshl_add_u64 v[46:47], s[24:25], 0, v[46:47]
	global_load_dword v78, v[46:47], off
	global_load_dword v201, v[44:45], off offset:64
	global_load_dword v221, v[46:47], off offset:64
	global_load_dword v202, v[44:45], off offset:128
	global_load_dword v222, v[46:47], off offset:128
	global_load_dword v203, v[44:45], off offset:192
	global_load_dword v223, v[46:47], off offset:192
	global_load_dword v204, v[44:45], off offset:256
	global_load_dword v224, v[46:47], off offset:256
	global_load_dword v205, v[44:45], off offset:320
	global_load_dword v225, v[46:47], off offset:320
	global_load_dword v206, v[44:45], off offset:384
	global_load_dword v226, v[46:47], off offset:384
	global_load_dword v207, v[44:45], off offset:448
	global_load_dword v227, v[46:47], off offset:448
	global_load_dword v208, v[44:45], off offset:512
	global_load_dword v228, v[46:47], off offset:512
	global_load_dword v209, v[44:45], off offset:576
	global_load_dword v229, v[46:47], off offset:576
	global_load_dword v210, v[44:45], off offset:640
	global_load_dword v230, v[46:47], off offset:640
	global_load_dword v211, v[44:45], off offset:704
	global_load_dword v231, v[46:47], off offset:704
	global_load_dword v212, v[44:45], off offset:768
	global_load_dword v232, v[46:47], off offset:768
	global_load_dword v213, v[44:45], off offset:832
	global_load_dword v233, v[46:47], off offset:832
	global_load_dword v214, v[44:45], off offset:896
	global_load_dword v234, v[46:47], off offset:896
	global_load_dword v215, v[44:45], off offset:960
	global_load_dword v235, v[46:47], off offset:960
	v_sub_f32_e32 v70, v70, v41
	v_sub_f32_e32 v71, v71, v39
	v_sub_f32_e32 v72, v72, v37
	v_sub_f32_e32 v73, v73, v35
	v_sub_f32_e32 v74, v74, v33
	v_sub_f32_e32 v75, v75, v31
	v_sub_f32_e32 v76, v76, v29
	v_sub_f32_e32 v77, v77, v43
	s_waitcnt vmcnt(0)
	v_mul_f32_e32 v79, v40, v53
	v_fma_f32 v70, v70, v79, v78
	v_mul_f32_e32 v79, v38, v53
	v_fma_f32 v71, v71, v79, v78
	v_mul_f32_e32 v79, v36, v53
	v_fma_f32 v72, v72, v79, v78
	v_mul_f32_e32 v79, v34, v53
	v_fma_f32 v73, v73, v79, v78
	v_mul_f32_e32 v79, v32, v53
	v_fma_f32 v74, v74, v79, v78
	v_mul_f32_e32 v79, v30, v53
	v_fma_f32 v75, v75, v79, v78
	v_mul_f32_e32 v79, v28, v53
	v_mul_f32_e32 v53, v42, v53
	v_fma_f32 v76, v76, v79, v78
	v_fmac_f32_e32 v78, v77, v53
	v_cvt_pk_bf16_f32 v70, v70, v71
	v_cvt_pk_bf16_f32 v71, v72, v73
	v_cvt_pk_bf16_f32 v72, v74, v75
	v_cvt_pk_bf16_f32 v73, v76, v78
	global_store_dwordx4 v[66:67], v[70:73], off
	s_nop 2
	v_mov_b32_e32 v71, v201
	s_nop 0
	v_mov_b32_e32 v72, v221
	v_lshlrev_b32_e32 v53, 16, v24
	v_and_b32_e32 v24, 0xffff0000, v24
	v_sub_f32_e32 v53, v53, v41
	v_lshlrev_b32_e32 v66, 16, v25
	v_sub_f32_e32 v24, v24, v39
	v_and_b32_e32 v25, 0xffff0000, v25
	v_sub_f32_e32 v66, v66, v37
	v_lshlrev_b32_e32 v67, 16, v26
	v_sub_f32_e32 v25, v25, v35
	v_and_b32_e32 v26, 0xffff0000, v26
	v_sub_f32_e32 v67, v67, v33
	v_lshlrev_b32_e32 v70, 16, v27
	v_and_b32_e32 v27, 0xffff0000, v27
	v_sub_f32_e32 v26, v26, v31
	v_sub_f32_e32 v70, v70, v29
	v_sub_f32_e32 v27, v27, v43
	v_mul_f32_e32 v73, v40, v71
	v_fma_f32 v53, v53, v73, v72
	v_mul_f32_e32 v73, v38, v71
	v_fma_f32 v24, v24, v73, v72
	v_mul_f32_e32 v73, v36, v71
	v_fma_f32 v66, v66, v73, v72
	v_mul_f32_e32 v73, v34, v71
	v_fma_f32 v25, v25, v73, v72
	v_mul_f32_e32 v73, v32, v71
	v_fma_f32 v67, v67, v73, v72
	v_mul_f32_e32 v73, v30, v71
	v_fma_f32 v26, v26, v73, v72
	v_mul_f32_e32 v73, v28, v71
	v_mul_f32_e32 v71, v42, v71
	v_fma_f32 v70, v70, v73, v72
	v_fmac_f32_e32 v72, v27, v71
	v_cvt_pk_bf16_f32 v24, v53, v24
	v_cvt_pk_bf16_f32 v25, v66, v25
	v_cvt_pk_bf16_f32 v26, v67, v26
	v_cvt_pk_bf16_f32 v27, v70, v72
	global_store_dwordx4 v[64:65], v[24:27], off
	s_nop 2
	v_mov_b32_e32 v53, v202
	s_nop 0
	v_mov_b32_e32 v64, v222
	v_lshlrev_b32_e32 v24, 16, v20
	v_and_b32_e32 v20, 0xffff0000, v20
	v_sub_f32_e32 v24, v24, v41
	v_lshlrev_b32_e32 v25, 16, v21
	v_sub_f32_e32 v20, v20, v39
	v_and_b32_e32 v21, 0xffff0000, v21
	v_sub_f32_e32 v25, v25, v37
	v_lshlrev_b32_e32 v26, 16, v22
	v_sub_f32_e32 v21, v21, v35
	v_and_b32_e32 v22, 0xffff0000, v22
	v_sub_f32_e32 v26, v26, v33
	v_lshlrev_b32_e32 v27, 16, v23
	v_and_b32_e32 v23, 0xffff0000, v23
	v_sub_f32_e32 v22, v22, v31
	v_sub_f32_e32 v27, v27, v29
	v_sub_f32_e32 v23, v23, v43
	v_mul_f32_e32 v65, v40, v53
	v_fma_f32 v24, v24, v65, v64
	v_mul_f32_e32 v65, v38, v53
	v_fma_f32 v20, v20, v65, v64
	v_mul_f32_e32 v65, v36, v53
	v_fma_f32 v25, v25, v65, v64
	v_mul_f32_e32 v65, v34, v53
	v_fma_f32 v21, v21, v65, v64
	v_mul_f32_e32 v65, v32, v53
	v_fma_f32 v26, v26, v65, v64
	v_mul_f32_e32 v65, v30, v53
	v_fma_f32 v22, v22, v65, v64
	v_mul_f32_e32 v65, v28, v53
	v_mul_f32_e32 v53, v42, v53
	v_fma_f32 v27, v27, v65, v64
	v_fmac_f32_e32 v64, v23, v53
	v_cvt_pk_bf16_f32 v20, v24, v20
	v_cvt_pk_bf16_f32 v21, v25, v21
	v_cvt_pk_bf16_f32 v22, v26, v22
	v_cvt_pk_bf16_f32 v23, v27, v64
	global_store_dwordx4 v[62:63], v[20:23], off
	s_nop 2
	v_mov_b32_e32 v24, v203
	v_mov_b32_e32 v25, v223
	v_lshlrev_b32_e32 v20, 16, v16
	v_and_b32_e32 v16, 0xffff0000, v16
	v_sub_f32_e32 v20, v20, v41
	v_lshlrev_b32_e32 v21, 16, v17
	v_sub_f32_e32 v16, v16, v39
	v_and_b32_e32 v17, 0xffff0000, v17
	v_sub_f32_e32 v21, v21, v37
	v_lshlrev_b32_e32 v22, 16, v18
; __device__ __forceinline__ void unpack8(const u32x4 w, float* f) { f[0] = bf_lo(w.x); f[1] = bf_hi(w.x); f[2] = bf_lo(w.y); f[3] = bf_hi(w.y); f[4] = bf_lo(w.z); f[5] = bf_hi(w.z); f[6] = bf_lo(w.w); f[7] = bf_hi(w.w); }
; __device__ __forceinline__ u32x4 pack8(const float* f) { u32x4 w; w.x = cvt_pk_bf16(f[0], f[1]); w.y = cvt_pk_bf16(f[2], f[3]); w.z = cvt_pk_bf16(f[4], f[5]); w.w = cvt_pk_bf16(f[6], f[7]); return w; }
; __device__ __forceinline__ void gm_ln_block(bf16_t* Vt, const float* S1, const float* S2, const float* lng, const float* lnb, int c0, int t0, int tid) {
;     ...
; #pragma unroll
;     for (int k0 = 0; k0 < 16; k0 += 8) {
;         u32x4 raw[8];
; #pragma unroll
;         for (int k = 0; k < 8; ++k) raw[k] = *(const u32x4*)(Vt + (size_t)(c0 + r0 + 16 * (k0 + k)) * MALL + tt);
; #pragma unroll
;         for (int k = 0; k < 8; ++k) { const int c = c0 + r0 + 16 * (k0 + k); float x[8]; unpack8(raw[k], x); const float g = lng[c], b = lnb[c];
; #pragma unroll
;             for (int e = 0; e < 8; ++e) x[e] = (x[e] - mu[e]) * (rs[e] * g) + b;
;             *(u32x4*)(Vt + (size_t)c * MALL + tt) = pack8(x); }
;     }
	v_sub_f32_e32 v17, v17, v35
	v_and_b32_e32 v18, 0xffff0000, v18
	v_sub_f32_e32 v22, v22, v33
	v_lshlrev_b32_e32 v23, 16, v19
	v_and_b32_e32 v19, 0xffff0000, v19
	v_sub_f32_e32 v18, v18, v31
	v_sub_f32_e32 v23, v23, v29
	v_sub_f32_e32 v19, v19, v43
	v_mul_f32_e32 v26, v40, v24
	v_fma_f32 v20, v20, v26, v25
	v_mul_f32_e32 v26, v38, v24
	v_fma_f32 v16, v16, v26, v25
	v_mul_f32_e32 v26, v36, v24
	v_fma_f32 v21, v21, v26, v25
	v_mul_f32_e32 v26, v34, v24
	v_fma_f32 v17, v17, v26, v25
	v_mul_f32_e32 v26, v32, v24
	v_fma_f32 v22, v22, v26, v25
	v_mul_f32_e32 v26, v30, v24
	v_fma_f32 v18, v18, v26, v25
	v_mul_f32_e32 v26, v28, v24
	v_mul_f32_e32 v24, v42, v24
	v_fma_f32 v23, v23, v26, v25
	v_fmac_f32_e32 v25, v19, v24
	v_cvt_pk_bf16_f32 v16, v20, v16
	v_cvt_pk_bf16_f32 v17, v21, v17
	v_cvt_pk_bf16_f32 v18, v22, v18
	v_cvt_pk_bf16_f32 v19, v23, v25
	global_store_dwordx4 v[60:61], v[16:19], off
	s_nop 2
	v_mov_b32_e32 v20, v204
	v_mov_b32_e32 v21, v224
	v_lshlrev_b32_e32 v16, 16, v12
	v_and_b32_e32 v12, 0xffff0000, v12
	v_sub_f32_e32 v16, v16, v41
	v_lshlrev_b32_e32 v17, 16, v13
	v_sub_f32_e32 v12, v12, v39
	v_and_b32_e32 v13, 0xffff0000, v13
	v_sub_f32_e32 v17, v17, v37
	v_lshlrev_b32_e32 v18, 16, v14
	v_sub_f32_e32 v13, v13, v35
	v_and_b32_e32 v14, 0xffff0000, v14
	v_sub_f32_e32 v18, v18, v33
	v_lshlrev_b32_e32 v19, 16, v15
	v_and_b32_e32 v15, 0xffff0000, v15
	v_sub_f32_e32 v14, v14, v31
	v_sub_f32_e32 v19, v19, v29
	v_sub_f32_e32 v15, v15, v43
	v_mul_f32_e32 v22, v40, v20
	v_fma_f32 v16, v16, v22, v21
	v_mul_f32_e32 v22, v38, v20
	v_fma_f32 v12, v12, v22, v21
	v_mul_f32_e32 v22, v36, v20
	v_fma_f32 v17, v17, v22, v21
	v_mul_f32_e32 v22, v34, v20
	v_fma_f32 v13, v13, v22, v21
	v_mul_f32_e32 v22, v32, v20
	v_fma_f32 v18, v18, v22, v21
	v_mul_f32_e32 v22, v30, v20
	v_fma_f32 v14, v14, v22, v21
	v_mul_f32_e32 v22, v28, v20
	v_mul_f32_e32 v20, v42, v20
	v_fma_f32 v19, v19, v22, v21
	v_fmac_f32_e32 v21, v15, v20
	v_cvt_pk_bf16_f32 v12, v16, v12
	v_cvt_pk_bf16_f32 v13, v17, v13
	v_cvt_pk_bf16_f32 v14, v18, v14
	v_cvt_pk_bf16_f32 v15, v19, v21
	global_store_dwordx4 v[58:59], v[12:15], off
	s_nop 2
	v_mov_b32_e32 v16, v205
	v_mov_b32_e32 v17, v225
	v_lshlrev_b32_e32 v12, 16, v8
	v_and_b32_e32 v8, 0xffff0000, v8
	v_sub_f32_e32 v12, v12, v41
	v_lshlrev_b32_e32 v13, 16, v9
	v_sub_f32_e32 v8, v8, v39
	v_and_b32_e32 v9, 0xffff0000, v9
	v_sub_f32_e32 v13, v13, v37
	v_lshlrev_b32_e32 v14, 16, v10
	v_sub_f32_e32 v9, v9, v35
	v_and_b32_e32 v10, 0xffff0000, v10
	v_sub_f32_e32 v14, v14, v33
	v_lshlrev_b32_e32 v15, 16, v11
	v_and_b32_e32 v11, 0xffff0000, v11
	v_sub_f32_e32 v10, v10, v31
	v_sub_f32_e32 v15, v15, v29
	v_sub_f32_e32 v11, v11, v43
	v_mul_f32_e32 v18, v40, v16
	v_fma_f32 v12, v12, v18, v17
	v_mul_f32_e32 v18, v38, v16
	v_fma_f32 v8, v8, v18, v17
	v_mul_f32_e32 v18, v36, v16
	v_fma_f32 v13, v13, v18, v17
	v_mul_f32_e32 v18, v34, v16
	v_fma_f32 v9, v9, v18, v17
	v_mul_f32_e32 v18, v32, v16
	v_fma_f32 v14, v14, v18, v17
	v_mul_f32_e32 v18, v30, v16
	v_fma_f32 v10, v10, v18, v17
	v_mul_f32_e32 v18, v28, v16
	v_mul_f32_e32 v16, v42, v16
	v_fma_f32 v15, v15, v18, v17
	v_fmac_f32_e32 v17, v11, v16
	v_cvt_pk_bf16_f32 v8, v12, v8
	v_cvt_pk_bf16_f32 v9, v13, v9
	v_cvt_pk_bf16_f32 v10, v14, v10
	v_cvt_pk_bf16_f32 v11, v15, v17
	global_store_dwordx4 v[56:57], v[8:11], off
	s_nop 2
	v_mov_b32_e32 v12, v206
	v_mov_b32_e32 v13, v226
	v_lshlrev_b32_e32 v8, 16, v4
	v_and_b32_e32 v4, 0xffff0000, v4
	v_sub_f32_e32 v8, v8, v41
	v_lshlrev_b32_e32 v9, 16, v5
	v_sub_f32_e32 v4, v4, v39
	v_and_b32_e32 v5, 0xffff0000, v5
	v_sub_f32_e32 v9, v9, v37
	v_lshlrev_b32_e32 v10, 16, v6
	v_sub_f32_e32 v5, v5, v35
	v_and_b32_e32 v6, 0xffff0000, v6
	v_sub_f32_e32 v10, v10, v33
	v_lshlrev_b32_e32 v11, 16, v7
	v_and_b32_e32 v7, 0xffff0000, v7
	v_sub_f32_e32 v6, v6, v31
	v_sub_f32_e32 v11, v11, v29
	v_sub_f32_e32 v7, v7, v43
	v_mul_f32_e32 v14, v40, v12
	v_fma_f32 v8, v8, v14, v13
	v_mul_f32_e32 v14, v38, v12
	v_fma_f32 v4, v4, v14, v13
	v_mul_f32_e32 v14, v36, v12
	v_fma_f32 v9, v9, v14, v13
	v_mul_f32_e32 v14, v34, v12
	v_fma_f32 v5, v5, v14, v13
	v_mul_f32_e32 v14, v32, v12
	v_fma_f32 v10, v10, v14, v13
	v_mul_f32_e32 v14, v30, v12
	v_fma_f32 v6, v6, v14, v13
	v_mul_f32_e32 v14, v28, v12
	v_mul_f32_e32 v12, v42, v12
	v_fma_f32 v11, v11, v14, v13
	v_fmac_f32_e32 v13, v7, v12
	v_cvt_pk_bf16_f32 v4, v8, v4
	v_cvt_pk_bf16_f32 v5, v9, v5
	v_cvt_pk_bf16_f32 v6, v10, v6
	v_cvt_pk_bf16_f32 v7, v11, v13
	global_store_dwordx4 v[54:55], v[4:7], off
	s_nop 2
	v_mov_b32_e32 v8, v207
	v_mov_b32_e32 v9, v227
	v_lshlrev_b32_e32 v4, 16, v0
	v_and_b32_e32 v0, 0xffff0000, v0
	v_sub_f32_e32 v4, v4, v41
	v_lshlrev_b32_e32 v5, 16, v1
	v_sub_f32_e32 v0, v0, v39
	v_and_b32_e32 v1, 0xffff0000, v1
	v_sub_f32_e32 v5, v5, v37
	v_lshlrev_b32_e32 v6, 16, v2
	v_sub_f32_e32 v1, v1, v35
	v_and_b32_e32 v2, 0xffff0000, v2
	v_sub_f32_e32 v6, v6, v33
	v_lshlrev_b32_e32 v7, 16, v3
	v_and_b32_e32 v3, 0xffff0000, v3
	v_sub_f32_e32 v2, v2, v31
	v_sub_f32_e32 v7, v7, v29
	v_sub_f32_e32 v3, v3, v43
	v_mul_f32_e32 v10, v40, v8
	v_fma_f32 v4, v4, v10, v9
	v_mul_f32_e32 v10, v38, v8
	v_fma_f32 v0, v0, v10, v9
	v_mul_f32_e32 v10, v36, v8
	v_fma_f32 v5, v5, v10, v9
	v_mul_f32_e32 v10, v34, v8
	v_fma_f32 v1, v1, v10, v9
	v_mul_f32_e32 v10, v32, v8
	v_fma_f32 v6, v6, v10, v9
	v_mul_f32_e32 v10, v30, v8
	v_fma_f32 v2, v2, v10, v9
	v_mul_f32_e32 v10, v28, v8
	v_mul_f32_e32 v8, v42, v8
	v_cvt_pk_bf16_f32 v0, v4, v0
	v_fma_f32 v7, v7, v10, v9
	v_fmac_f32_e32 v9, v3, v8
	v_cvt_pk_bf16_f32 v1, v5, v1
	v_cvt_pk_bf16_f32 v2, v6, v2
	v_cvt_pk_bf16_f32 v3, v7, v9
	global_store_dwordx4 v[50:51], v[0:3], off
	s_nop 1
	v_add_u32_e32 v0, 0x80, v52
	v_mad_i64_i32 v[64:65], s[2:3], v0, s6, v[48:49]
	v_add_u32_e32 v0, 0x90, v52
	v_mad_i64_i32 v[62:63], s[2:3], v0, s6, v[48:49]
	v_add_u32_e32 v0, 0xa0, v52
	v_mad_i64_i32 v[60:61], s[2:3], v0, s6, v[48:49]
	v_add_u32_e32 v0, 0xb0, v52
	v_mad_i64_i32 v[58:59], s[2:3], v0, s6, v[48:49]
	v_add_u32_e32 v0, 0xc0, v52
	v_mad_i64_i32 v[56:57], s[2:3], v0, s6, v[48:49]
	v_add_u32_e32 v0, 0xd0, v52
	v_mad_i64_i32 v[54:55], s[2:3], v0, s6, v[48:49]
	v_add_u32_e32 v0, 0xe0, v52
	global_load_dwordx4 v[70:73], v[64:65], off
	global_load_dwordx4 v[24:27], v[62:63], off
	v_mad_i64_i32 v[50:51], s[2:3], v0, s6, v[48:49]
	v_add_u32_e32 v0, 0xf0, v52
	v_mad_i64_i32 v[48:49], s[2:3], v0, s6, v[48:49]
	global_load_dwordx4 v[20:23], v[60:61], off
	global_load_dwordx4 v[16:19], v[58:59], off
	global_load_dwordx4 v[12:15], v[56:57], off
	global_load_dwordx4 v[8:11], v[54:55], off
	global_load_dwordx4 v[4:7], v[50:51], off
	global_load_dwordx4 v[0:3], v[48:49], off
	s_nop 2
	v_mov_b32_e32 v74, v208
	v_mov_b32_e32 v75, v228
	s_mov_b64 s[6:7], 0
	s_waitcnt vmcnt(7)
; __device__ __forceinline__ void unpack8(const u32x4 w, float* f) { f[0] = bf_lo(w.x); f[1] = bf_hi(w.x); f[2] = bf_lo(w.y); f[3] = bf_hi(w.y); f[4] = bf_lo(w.z); f[5] = bf_hi(w.z); f[6] = bf_lo(w.w); f[7] = bf_hi(w.w); }
; __device__ __forceinline__ u32x4 pack8(const float* f) { u32x4 w; w.x = cvt_pk_bf16(f[0], f[1]); w.y = cvt_pk_bf16(f[2], f[3]); w.z = cvt_pk_bf16(f[4], f[5]); w.w = cvt_pk_bf16(f[6], f[7]); return w; }
; __device__ __forceinline__ void gm_ln_block(bf16_t* Vt, const float* S1, const float* S2, const float* lng, const float* lnb, int c0, int t0, int tid) {
;     ...
; #pragma unroll
;     for (int k0 = 0; k0 < 16; k0 += 8) {
;         u32x4 raw[8];
; #pragma unroll
;         for (int k = 0; k < 8; ++k) raw[k] = *(const u32x4*)(Vt + (size_t)(c0 + r0 + 16 * (k0 + k)) * MALL + tt);
; #pragma unroll
;         for (int k = 0; k < 8; ++k) { const int c = c0 + r0 + 16 * (k0 + k); float x[8]; unpack8(raw[k], x); const float g = lng[c], b = lnb[c];
; #pragma unroll
;             for (int e = 0; e < 8; ++e) x[e] = (x[e] - mu[e]) * (rs[e] * g) + b;
;             *(u32x4*)(Vt + (size_t)c * MALL + tt) = pack8(x); }
;     }
	v_lshlrev_b32_e32 v52, 16, v70
	v_and_b32_e32 v53, 0xffff0000, v70
	v_sub_f32_e32 v52, v52, v41
	v_lshlrev_b32_e32 v66, 16, v71
	v_sub_f32_e32 v53, v53, v39
	v_and_b32_e32 v67, 0xffff0000, v71
	v_sub_f32_e32 v66, v66, v37
	v_lshlrev_b32_e32 v70, 16, v72
	v_sub_f32_e32 v67, v67, v35
	v_and_b32_e32 v71, 0xffff0000, v72
	v_sub_f32_e32 v70, v70, v33
	v_lshlrev_b32_e32 v72, 16, v73
	s_waitcnt vmcnt(0)
	v_mul_f32_e32 v76, v40, v74
	v_fma_f32 v52, v52, v76, v75
	v_mul_f32_e32 v76, v38, v74
	v_fma_f32 v53, v53, v76, v75
	v_mul_f32_e32 v76, v36, v74
	v_fma_f32 v66, v66, v76, v75
	v_mul_f32_e32 v76, v34, v74
	v_fma_f32 v67, v67, v76, v75
	v_mul_f32_e32 v76, v32, v74
	v_fma_f32 v76, v70, v76, v75
	v_sub_f32_e32 v70, v71, v31
	v_mul_f32_e32 v71, v30, v74
	v_and_b32_e32 v73, 0xffff0000, v73
	v_fma_f32 v77, v70, v71, v75
	v_sub_f32_e32 v70, v72, v29
	v_mul_f32_e32 v71, v28, v74
	v_fma_f32 v78, v70, v71, v75
	v_sub_f32_e32 v70, v73, v43
	v_mul_f32_e32 v71, v42, v74
	v_fmac_f32_e32 v75, v70, v71
	v_cvt_pk_bf16_f32 v70, v52, v53
	v_cvt_pk_bf16_f32 v71, v66, v67
	v_cvt_pk_bf16_f32 v72, v76, v77
	v_cvt_pk_bf16_f32 v73, v78, v75
	global_store_dwordx4 v[64:65], v[70:73], off
	s_nop 2
	v_mov_b32_e32 v66, v209
	v_mov_b32_e32 v67, v229
	v_lshlrev_b32_e32 v52, 16, v24
	v_and_b32_e32 v24, 0xffff0000, v24
	v_sub_f32_e32 v52, v52, v41
	v_lshlrev_b32_e32 v53, 16, v25
	v_sub_f32_e32 v24, v24, v39
	v_and_b32_e32 v25, 0xffff0000, v25
	v_sub_f32_e32 v53, v53, v37
	v_lshlrev_b32_e32 v64, 16, v26
	v_sub_f32_e32 v25, v25, v35
	v_and_b32_e32 v26, 0xffff0000, v26
	v_sub_f32_e32 v64, v64, v33
	v_lshlrev_b32_e32 v65, 16, v27
	v_and_b32_e32 v27, 0xffff0000, v27
	v_sub_f32_e32 v26, v26, v31
	v_sub_f32_e32 v65, v65, v29
	v_sub_f32_e32 v27, v27, v43
	v_mul_f32_e32 v70, v40, v66
	v_fma_f32 v52, v52, v70, v67
	v_mul_f32_e32 v70, v38, v66
	v_fma_f32 v24, v24, v70, v67
	v_mul_f32_e32 v70, v36, v66
	v_fma_f32 v53, v53, v70, v67
	v_mul_f32_e32 v70, v34, v66
	v_fma_f32 v25, v25, v70, v67
	v_mul_f32_e32 v70, v32, v66
	v_fma_f32 v64, v64, v70, v67
	v_mul_f32_e32 v70, v30, v66
	v_fma_f32 v26, v26, v70, v67
	v_mul_f32_e32 v70, v28, v66
	v_mul_f32_e32 v66, v42, v66
	v_fma_f32 v65, v65, v70, v67
	v_fmac_f32_e32 v67, v27, v66
	v_cvt_pk_bf16_f32 v24, v52, v24
	v_cvt_pk_bf16_f32 v25, v53, v25
	v_cvt_pk_bf16_f32 v26, v64, v26
	v_cvt_pk_bf16_f32 v27, v65, v67
	global_store_dwordx4 v[62:63], v[24:27], off
	s_nop 2
	v_mov_b32_e32 v52, v210
	v_mov_b32_e32 v53, v230
	v_lshlrev_b32_e32 v24, 16, v20
	v_and_b32_e32 v20, 0xffff0000, v20
	v_sub_f32_e32 v24, v24, v41
	v_lshlrev_b32_e32 v25, 16, v21
	v_sub_f32_e32 v20, v20, v39
	v_and_b32_e32 v21, 0xffff0000, v21
	v_sub_f32_e32 v25, v25, v37
	v_lshlrev_b32_e32 v26, 16, v22
	v_sub_f32_e32 v21, v21, v35
	v_and_b32_e32 v22, 0xffff0000, v22
	v_sub_f32_e32 v26, v26, v33
	v_lshlrev_b32_e32 v27, 16, v23
	v_and_b32_e32 v23, 0xffff0000, v23
	v_sub_f32_e32 v22, v22, v31
	v_sub_f32_e32 v27, v27, v29
	v_sub_f32_e32 v23, v23, v43
	v_mul_f32_e32 v62, v40, v52
	v_fma_f32 v24, v24, v62, v53
	v_mul_f32_e32 v62, v38, v52
	v_fma_f32 v20, v20, v62, v53
	v_mul_f32_e32 v62, v36, v52
	v_fma_f32 v25, v25, v62, v53
	v_mul_f32_e32 v62, v34, v52
	v_fma_f32 v21, v21, v62, v53
	v_mul_f32_e32 v62, v32, v52
	v_fma_f32 v26, v26, v62, v53
	v_mul_f32_e32 v62, v30, v52
	v_fma_f32 v22, v22, v62, v53
	v_mul_f32_e32 v62, v28, v52
	v_mul_f32_e32 v52, v42, v52
	v_fma_f32 v27, v27, v62, v53
	v_fmac_f32_e32 v53, v23, v52
	v_cvt_pk_bf16_f32 v20, v24, v20
	v_cvt_pk_bf16_f32 v21, v25, v21
	v_cvt_pk_bf16_f32 v22, v26, v22
	v_cvt_pk_bf16_f32 v23, v27, v53
	global_store_dwordx4 v[60:61], v[20:23], off
	s_nop 2
	v_mov_b32_e32 v24, v211
	v_mov_b32_e32 v25, v231
	v_lshlrev_b32_e32 v20, 16, v16
	v_and_b32_e32 v16, 0xffff0000, v16
	v_sub_f32_e32 v20, v20, v41
	v_lshlrev_b32_e32 v21, 16, v17
	v_sub_f32_e32 v16, v16, v39
	v_and_b32_e32 v17, 0xffff0000, v17
	v_sub_f32_e32 v21, v21, v37
	v_lshlrev_b32_e32 v22, 16, v18
	v_sub_f32_e32 v17, v17, v35
	v_and_b32_e32 v18, 0xffff0000, v18
	v_sub_f32_e32 v22, v22, v33
	v_lshlrev_b32_e32 v23, 16, v19
	v_and_b32_e32 v19, 0xffff0000, v19
	v_sub_f32_e32 v18, v18, v31
	v_sub_f32_e32 v23, v23, v29
	v_sub_f32_e32 v19, v19, v43
	v_mul_f32_e32 v26, v40, v24
	v_fma_f32 v20, v20, v26, v25
	v_mul_f32_e32 v26, v38, v24
	v_fma_f32 v16, v16, v26, v25
	v_mul_f32_e32 v26, v36, v24
	v_fma_f32 v21, v21, v26, v25
	v_mul_f32_e32 v26, v34, v24
	v_fma_f32 v17, v17, v26, v25
	v_mul_f32_e32 v26, v32, v24
	v_fma_f32 v22, v22, v26, v25
	v_mul_f32_e32 v26, v30, v24
	v_fma_f32 v18, v18, v26, v25
	v_mul_f32_e32 v26, v28, v24
	v_mul_f32_e32 v24, v42, v24
	v_fma_f32 v23, v23, v26, v25
	v_fmac_f32_e32 v25, v19, v24
	v_cvt_pk_bf16_f32 v16, v20, v16
	v_cvt_pk_bf16_f32 v17, v21, v17
	v_cvt_pk_bf16_f32 v18, v22, v18
	v_cvt_pk_bf16_f32 v19, v23, v25
; __device__ __forceinline__ void unpack8(const u32x4 w, float* f) { f[0] = bf_lo(w.x); f[1] = bf_hi(w.x); f[2] = bf_lo(w.y); f[3] = bf_hi(w.y); f[4] = bf_lo(w.z); f[5] = bf_hi(w.z); f[6] = bf_lo(w.w); f[7] = bf_hi(w.w); }
; __device__ __forceinline__ u32x4 pack8(const float* f) { u32x4 w; w.x = cvt_pk_bf16(f[0], f[1]); w.y = cvt_pk_bf16(f[2], f[3]); w.z = cvt_pk_bf16(f[4], f[5]); w.w = cvt_pk_bf16(f[6], f[7]); return w; }
; __device__ __forceinline__ void gm_ln_block(bf16_t* Vt, const float* S1, const float* S2, const float* lng, const float* lnb, int c0, int t0, int tid) {
;     ...
; #pragma unroll
;     for (int k0 = 0; k0 < 16; k0 += 8) {
;         u32x4 raw[8];
; #pragma unroll
;         for (int k = 0; k < 8; ++k) raw[k] = *(const u32x4*)(Vt + (size_t)(c0 + r0 + 16 * (k0 + k)) * MALL + tt);
; #pragma unroll
;         for (int k = 0; k < 8; ++k) { const int c = c0 + r0 + 16 * (k0 + k); float x[8]; unpack8(raw[k], x); const float g = lng[c], b = lnb[c];
; #pragma unroll
;             for (int e = 0; e < 8; ++e) x[e] = (x[e] - mu[e]) * (rs[e] * g) + b;
;             *(u32x4*)(Vt + (size_t)c * MALL + tt) = pack8(x); }
;     }
	global_store_dwordx4 v[58:59], v[16:19], off
	s_nop 2
	v_mov_b32_e32 v20, v212
	v_mov_b32_e32 v21, v232
	v_lshlrev_b32_e32 v16, 16, v12
	v_and_b32_e32 v12, 0xffff0000, v12
	v_sub_f32_e32 v16, v16, v41
	v_lshlrev_b32_e32 v17, 16, v13
	v_sub_f32_e32 v12, v12, v39
	v_and_b32_e32 v13, 0xffff0000, v13
	v_sub_f32_e32 v17, v17, v37
	v_lshlrev_b32_e32 v18, 16, v14
	v_sub_f32_e32 v13, v13, v35
	v_and_b32_e32 v14, 0xffff0000, v14
	v_sub_f32_e32 v18, v18, v33
	v_lshlrev_b32_e32 v19, 16, v15
	v_and_b32_e32 v15, 0xffff0000, v15
	v_sub_f32_e32 v14, v14, v31
	v_sub_f32_e32 v19, v19, v29
	v_sub_f32_e32 v15, v15, v43
	v_mul_f32_e32 v22, v40, v20
	v_fma_f32 v16, v16, v22, v21
	v_mul_f32_e32 v22, v38, v20
	v_fma_f32 v12, v12, v22, v21
	v_mul_f32_e32 v22, v36, v20
	v_fma_f32 v17, v17, v22, v21
	v_mul_f32_e32 v22, v34, v20
	v_fma_f32 v13, v13, v22, v21
	v_mul_f32_e32 v22, v32, v20
	v_fma_f32 v18, v18, v22, v21
	v_mul_f32_e32 v22, v30, v20
	v_fma_f32 v14, v14, v22, v21
	v_mul_f32_e32 v22, v28, v20
	v_mul_f32_e32 v20, v42, v20
	v_fma_f32 v19, v19, v22, v21
	v_fmac_f32_e32 v21, v15, v20
	v_cvt_pk_bf16_f32 v12, v16, v12
	v_cvt_pk_bf16_f32 v13, v17, v13
	v_cvt_pk_bf16_f32 v14, v18, v14
	v_cvt_pk_bf16_f32 v15, v19, v21
	global_store_dwordx4 v[56:57], v[12:15], off
	s_nop 2
	v_mov_b32_e32 v16, v213
	v_mov_b32_e32 v17, v233
	v_lshlrev_b32_e32 v12, 16, v8
	v_and_b32_e32 v8, 0xffff0000, v8
	v_sub_f32_e32 v12, v12, v41
	v_lshlrev_b32_e32 v13, 16, v9
	v_sub_f32_e32 v8, v8, v39
	v_and_b32_e32 v9, 0xffff0000, v9
	v_sub_f32_e32 v13, v13, v37
	v_lshlrev_b32_e32 v14, 16, v10
	v_sub_f32_e32 v9, v9, v35
	v_and_b32_e32 v10, 0xffff0000, v10
	v_sub_f32_e32 v14, v14, v33
	v_lshlrev_b32_e32 v15, 16, v11
	v_and_b32_e32 v11, 0xffff0000, v11
	v_sub_f32_e32 v10, v10, v31
	v_sub_f32_e32 v15, v15, v29
	v_sub_f32_e32 v11, v11, v43
	v_mul_f32_e32 v18, v40, v16
	v_fma_f32 v12, v12, v18, v17
	v_mul_f32_e32 v18, v38, v16
	v_fma_f32 v8, v8, v18, v17
	v_mul_f32_e32 v18, v36, v16
	v_fma_f32 v13, v13, v18, v17
	v_mul_f32_e32 v18, v34, v16
	v_fma_f32 v9, v9, v18, v17
	v_mul_f32_e32 v18, v32, v16
	v_fma_f32 v14, v14, v18, v17
	v_mul_f32_e32 v18, v30, v16
	v_fma_f32 v10, v10, v18, v17
	v_mul_f32_e32 v18, v28, v16
	v_mul_f32_e32 v16, v42, v16
	v_fma_f32 v15, v15, v18, v17
	v_fmac_f32_e32 v17, v11, v16
	v_cvt_pk_bf16_f32 v8, v12, v8
	v_cvt_pk_bf16_f32 v9, v13, v9
	v_cvt_pk_bf16_f32 v10, v14, v10
	v_cvt_pk_bf16_f32 v11, v15, v17
	global_store_dwordx4 v[54:55], v[8:11], off
	s_nop 2
	v_mov_b32_e32 v12, v214
	v_mov_b32_e32 v13, v234
	v_lshlrev_b32_e32 v8, 16, v4
	v_and_b32_e32 v4, 0xffff0000, v4
	v_sub_f32_e32 v8, v8, v41
	v_lshlrev_b32_e32 v9, 16, v5
	v_sub_f32_e32 v4, v4, v39
	v_and_b32_e32 v5, 0xffff0000, v5
	v_sub_f32_e32 v9, v9, v37
	v_lshlrev_b32_e32 v10, 16, v6
	v_sub_f32_e32 v5, v5, v35
	v_and_b32_e32 v6, 0xffff0000, v6
	v_sub_f32_e32 v10, v10, v33
	v_lshlrev_b32_e32 v11, 16, v7
	v_and_b32_e32 v7, 0xffff0000, v7
	v_sub_f32_e32 v6, v6, v31
	v_sub_f32_e32 v11, v11, v29
	v_sub_f32_e32 v7, v7, v43
	v_mul_f32_e32 v14, v40, v12
	v_fma_f32 v8, v8, v14, v13
	v_mul_f32_e32 v14, v38, v12
	v_fma_f32 v4, v4, v14, v13
	v_mul_f32_e32 v14, v36, v12
	v_fma_f32 v9, v9, v14, v13
	v_mul_f32_e32 v14, v34, v12
	v_fma_f32 v5, v5, v14, v13
	v_mul_f32_e32 v14, v32, v12
	v_fma_f32 v10, v10, v14, v13
	v_mul_f32_e32 v14, v30, v12
	v_fma_f32 v6, v6, v14, v13
	v_mul_f32_e32 v14, v28, v12
	v_mul_f32_e32 v12, v42, v12
	v_fma_f32 v11, v11, v14, v13
	v_fmac_f32_e32 v13, v7, v12
	v_cvt_pk_bf16_f32 v4, v8, v4
	v_cvt_pk_bf16_f32 v5, v9, v5
	v_cvt_pk_bf16_f32 v6, v10, v6
	v_cvt_pk_bf16_f32 v7, v11, v13
	global_store_dwordx4 v[50:51], v[4:7], off
	s_nop 2
	v_mov_b32_e32 v8, v215
	v_mov_b32_e32 v9, v235
	v_lshlrev_b32_e32 v4, 16, v0
	v_and_b32_e32 v0, 0xffff0000, v0
	v_sub_f32_e32 v4, v4, v41
	v_lshlrev_b32_e32 v5, 16, v1
	v_sub_f32_e32 v0, v0, v39
	v_and_b32_e32 v1, 0xffff0000, v1
	v_sub_f32_e32 v5, v5, v37
	v_lshlrev_b32_e32 v6, 16, v2
	v_sub_f32_e32 v1, v1, v35
	v_and_b32_e32 v2, 0xffff0000, v2
	v_sub_f32_e32 v6, v6, v33
	v_lshlrev_b32_e32 v7, 16, v3
	v_and_b32_e32 v3, 0xffff0000, v3
	v_sub_f32_e32 v2, v2, v31
	v_sub_f32_e32 v7, v7, v29
	v_sub_f32_e32 v3, v3, v43
	v_mul_f32_e32 v10, v40, v8
	v_fma_f32 v4, v4, v10, v9
	v_mul_f32_e32 v10, v38, v8
	v_fma_f32 v0, v0, v10, v9
	v_mul_f32_e32 v10, v36, v8
	v_fma_f32 v5, v5, v10, v9
	v_mul_f32_e32 v10, v34, v8
	v_fma_f32 v1, v1, v10, v9
	v_mul_f32_e32 v10, v32, v8
	v_fma_f32 v6, v6, v10, v9
	v_mul_f32_e32 v10, v30, v8
	v_fma_f32 v2, v2, v10, v9
	v_mul_f32_e32 v10, v28, v8
	v_mul_f32_e32 v8, v42, v8
	v_fma_f32 v7, v7, v10, v9
	v_fmac_f32_e32 v9, v3, v8
	v_cvt_pk_bf16_f32 v0, v4, v0
	v_cvt_pk_bf16_f32 v1, v5, v1
	v_cvt_pk_bf16_f32 v2, v6, v2
	v_cvt_pk_bf16_f32 v3, v7, v9
	global_store_dwordx4 v[48:49], v[0:3], off
	s_branch .LBB0_420
